# ph10 long MLA units: unit-id bits 3 and 8 swapped so co-resident blocks stream the same (batch, head) K/V
# baseline (speedup 1.0000x reference)
.LBB0_1066:
	s_andn2_b64 vcc, exec, s[36:37]
	s_movk_i32 s43, 0x100
	s_cbranch_vccnz .LBB0_1068
	s_lshr_b32 s4, s42, 3
	s_lshr_b32 s30, s42, 8
	s_xor_b32 s4, s4, s30
	s_and_b32 s4, s4, 1
	s_mulk_i32 s4, 0x108
	s_xor_b32 s38, s42, s4
	s_lshl_b32 s4, s38, 2
	s_and_b32 s4, s4, 28
	s_ashr_i32 s30, s38, 7
	s_add_i32 s4, s4, s30
	s_ashr_i32 s31, s4, 3
	s_lshl_b32 s30, s38, 4
	s_and_b32 s38, s4, 7
	s_lshl_b32 s4, s31, 11
	s_and_b32 s30, s30, 0x780
	s_or_b32 s4, s4, s30
	v_add_u32_e32 v2, s4, v174
	s_mul_i32 s4, s31, 0x900
	s_add_i32 s30, s4, 0x1000
	s_mul_hi_i32 s4, s31, 0x240000
	s_mul_i32 s31, s31, 0x240000
	s_mul_i32 s34, s38, 0x48000
	s_add_u32 s31, s31, s34
	s_addc_u32 s4, s4, 0
	s_add_u32 s34, s31, 0x400000
	s_movk_i32 s43, 0x900
	s_addc_u32 s35, s4, 0
